# GEMM2 gate epilogue rewritten by hand: all 16 PG gate loads issued up front (one exposed latency instead of two per unit), f16 gates applied in place with v_fma_mix_f32 (f32 math, same numerics); on t
# speedup vs baseline: 1.0041x; 1.0041x over previous
;     __device__ __forceinline__ void operator()(f32x4 (&acc)[2][2][4][2], const Unit& u, int wr, int wc, int fr, int fq) const {
;         const int row0 = u.pm * BM + wr * 64 + fr, col0 = u.pn * BM + wc * 32 + 8 * fq;
;         const h16* gbase = PG + (size_t)(u.pm * 32 + 2 * u.pn) * 65536 + (u.half == 0 ? 0 : 32768) + (wr * 4 + wc) * 512 + (fq * 16 + fr) * 8;
; #pragma unroll
;         for (int ai = 0; ai < 2; ++ai) {
;             h16x8 gt[4][2];
; #pragma unroll
;             for (int m = 0; m < 4; ++m)
; #pragma unroll
;                 for (int bj = 0; bj < 2; ++bj) gt[m][bj] = *(const h16x8*)(gbase + (size_t)bj * 65536 + (ai * 4 + m) * 4096);
;             if (u.half == 0) {
; #pragma unroll
;                 for (int m = 0; m < 4; ++m)
; #pragma unroll
;                     for (int bj = 0; bj < 2; ++bj)
; #pragma unroll
;                         for (int j = 0; j < 4; ++j) { acc[ai][bj][m][0][j] *= (float)gt[m][bj][j]; acc[ai][bj][m][1][j] *= (float)gt[m][bj][4 + j]; }
.LBB0_474:
	s_lshl_b32 s4, s44, 5
	s_lshl_b32 s5, s45, 1
	s_add_i32 s4, s4, s5
	s_ashr_i32 s5, s4, 31
	s_lshl_b64 s[4:5], s[4:5], 17
	s_add_u32 s27, s61, s4
	s_addc_u32 s29, s62, s5
	s_cmp_lg_u32 s80, 0
	s_cselect_b64 s[46:47], -1, 0
	s_cmp_eq_u32 s80, 0
	s_cselect_b64 s[4:5], -1, 0
	s_and_b64 s[4:5], s[4:5], exec
	s_cselect_b32 s48, 0, 0x10000
	s_add_u32 s27, s27, s48
	s_addc_u32 s29, s29, 0
	s_add_u32 s48, s27, s18
	s_addc_u32 s49, s29, s19
	global_load_dwordx4 v[148:151], v132, s[48:49] nt
	v_add_u32_e32 v143, 0x20000, v132
	global_load_dwordx4 v[152:155], v143, s[48:49] nt
	v_add_u32_e32 v146, 0x2000, v132
	global_load_dwordx4 v[156:159], v146, s[48:49] nt
	v_add_u32_e32 v147, 0x22000, v132
	global_load_dwordx4 v[160:163], v147, s[48:49] nt
	v_add_u32_e32 v142, 0x4000, v132
	global_load_dwordx4 v[164:167], v142, s[48:49] nt
	v_add_u32_e32 v143, 0x24000, v132
	global_load_dwordx4 v[168:171], v143, s[48:49] nt
	v_add_u32_e32 v146, 0x6000, v132
	global_load_dwordx4 v[172:175], v146, s[48:49] nt
	v_add_u32_e32 v147, 0x26000, v132
	global_load_dwordx4 v[176:179], v147, s[48:49] nt
	v_add_u32_e32 v142, 0x8000, v132
	global_load_dwordx4 v[180:183], v142, s[48:49] nt
	v_add_u32_e32 v143, 0x28000, v132
	global_load_dwordx4 v[184:187], v143, s[48:49] nt
	v_add_u32_e32 v146, 0xa000, v132
	global_load_dwordx4 v[188:191], v146, s[48:49] nt
	v_add_u32_e32 v147, 0x2a000, v132
	global_load_dwordx4 v[192:195], v147, s[48:49] nt
	v_add_u32_e32 v142, 0xc000, v132
	global_load_dwordx4 v[196:199], v142, s[48:49] nt
	v_add_u32_e32 v143, 0x2c000, v132
	global_load_dwordx4 v[200:203], v143, s[48:49] nt
	v_add_u32_e32 v146, 0xe000, v132
	global_load_dwordx4 v[204:207], v146, s[48:49] nt
	v_add_u32_e32 v147, 0x2e000, v132
	global_load_dwordx4 v[208:211], v147, s[48:49] nt
	s_and_b64 vcc, exec, s[4:5]
	s_cbranch_vccz .Lg2e_final
	s_waitcnt vmcnt(15)
	v_fma_mix_f32 v124, v124, v148, v133 op_sel_hi:[0,1,0]
	v_fma_mix_f32 v125, v125, v148, v133 op_sel:[0,1,0] op_sel_hi:[0,1,0]
	v_fma_mix_f32 v126, v126, v149, v133 op_sel_hi:[0,1,0]
	v_fma_mix_f32 v127, v127, v149, v133 op_sel:[0,1,0] op_sel_hi:[0,1,0]
	v_fma_mix_f32 v120, v120, v150, v133 op_sel_hi:[0,1,0]
	v_fma_mix_f32 v121, v121, v150, v133 op_sel:[0,1,0] op_sel_hi:[0,1,0]
	v_fma_mix_f32 v122, v122, v151, v133 op_sel_hi:[0,1,0]
	v_fma_mix_f32 v123, v123, v151, v133 op_sel:[0,1,0] op_sel_hi:[0,1,0]
	s_waitcnt vmcnt(14)
	v_fma_mix_f32 v92, v92, v152, v133 op_sel_hi:[0,1,0]
	v_fma_mix_f32 v93, v93, v152, v133 op_sel:[0,1,0] op_sel_hi:[0,1,0]
	v_fma_mix_f32 v94, v94, v153, v133 op_sel_hi:[0,1,0]
	v_fma_mix_f32 v95, v95, v153, v133 op_sel:[0,1,0] op_sel_hi:[0,1,0]
	v_fma_mix_f32 v88, v88, v154, v133 op_sel_hi:[0,1,0]
	v_fma_mix_f32 v89, v89, v154, v133 op_sel:[0,1,0] op_sel_hi:[0,1,0]
	v_fma_mix_f32 v90, v90, v155, v133 op_sel_hi:[0,1,0]
	v_fma_mix_f32 v91, v91, v155, v133 op_sel:[0,1,0] op_sel_hi:[0,1,0]
	s_waitcnt vmcnt(13)
	v_fma_mix_f32 v116, v116, v156, v133 op_sel_hi:[0,1,0]
	v_fma_mix_f32 v117, v117, v156, v133 op_sel:[0,1,0] op_sel_hi:[0,1,0]
	v_fma_mix_f32 v118, v118, v157, v133 op_sel_hi:[0,1,0]
	v_fma_mix_f32 v119, v119, v157, v133 op_sel:[0,1,0] op_sel_hi:[0,1,0]
	v_fma_mix_f32 v112, v112, v158, v133 op_sel_hi:[0,1,0]
	v_fma_mix_f32 v113, v113, v158, v133 op_sel:[0,1,0] op_sel_hi:[0,1,0]
	v_fma_mix_f32 v114, v114, v159, v133 op_sel_hi:[0,1,0]
	v_fma_mix_f32 v115, v115, v159, v133 op_sel:[0,1,0] op_sel_hi:[0,1,0]
	s_waitcnt vmcnt(12)
	v_fma_mix_f32 v84, v84, v160, v133 op_sel_hi:[0,1,0]
	v_fma_mix_f32 v85, v85, v160, v133 op_sel:[0,1,0] op_sel_hi:[0,1,0]
	v_fma_mix_f32 v86, v86, v161, v133 op_sel_hi:[0,1,0]
	v_fma_mix_f32 v87, v87, v161, v133 op_sel:[0,1,0] op_sel_hi:[0,1,0]
	v_fma_mix_f32 v80, v80, v162, v133 op_sel_hi:[0,1,0]
	v_fma_mix_f32 v81, v81, v162, v133 op_sel:[0,1,0] op_sel_hi:[0,1,0]
	v_fma_mix_f32 v82, v82, v163, v133 op_sel_hi:[0,1,0]
	v_fma_mix_f32 v83, v83, v163, v133 op_sel:[0,1,0] op_sel_hi:[0,1,0]
	s_waitcnt vmcnt(11)
	v_fma_mix_f32 v108, v108, v164, v133 op_sel_hi:[0,1,0]
	v_fma_mix_f32 v109, v109, v164, v133 op_sel:[0,1,0] op_sel_hi:[0,1,0]
	v_fma_mix_f32 v110, v110, v165, v133 op_sel_hi:[0,1,0]
	v_fma_mix_f32 v111, v111, v165, v133 op_sel:[0,1,0] op_sel_hi:[0,1,0]
	v_fma_mix_f32 v104, v104, v166, v133 op_sel_hi:[0,1,0]
	v_fma_mix_f32 v105, v105, v166, v133 op_sel:[0,1,0] op_sel_hi:[0,1,0]
	v_fma_mix_f32 v106, v106, v167, v133 op_sel_hi:[0,1,0]
	v_fma_mix_f32 v107, v107, v167, v133 op_sel:[0,1,0] op_sel_hi:[0,1,0]
	s_waitcnt vmcnt(10)
	v_fma_mix_f32 v76, v76, v168, v133 op_sel_hi:[0,1,0]
	v_fma_mix_f32 v77, v77, v168, v133 op_sel:[0,1,0] op_sel_hi:[0,1,0]
	v_fma_mix_f32 v78, v78, v169, v133 op_sel_hi:[0,1,0]
	v_fma_mix_f32 v79, v79, v169, v133 op_sel:[0,1,0] op_sel_hi:[0,1,0]
	v_fma_mix_f32 v72, v72, v170, v133 op_sel_hi:[0,1,0]
	v_fma_mix_f32 v73, v73, v170, v133 op_sel:[0,1,0] op_sel_hi:[0,1,0]
	v_fma_mix_f32 v74, v74, v171, v133 op_sel_hi:[0,1,0]
	v_fma_mix_f32 v75, v75, v171, v133 op_sel:[0,1,0] op_sel_hi:[0,1,0]
	s_waitcnt vmcnt(9)
	v_fma_mix_f32 v100, v100, v172, v133 op_sel_hi:[0,1,0]
	v_fma_mix_f32 v101, v101, v172, v133 op_sel:[0,1,0] op_sel_hi:[0,1,0]
	v_fma_mix_f32 v102, v102, v173, v133 op_sel_hi:[0,1,0]
	v_fma_mix_f32 v103, v103, v173, v133 op_sel:[0,1,0] op_sel_hi:[0,1,0]
	v_fma_mix_f32 v96, v96, v174, v133 op_sel_hi:[0,1,0]
	v_fma_mix_f32 v97, v97, v174, v133 op_sel:[0,1,0] op_sel_hi:[0,1,0]
	v_fma_mix_f32 v98, v98, v175, v133 op_sel_hi:[0,1,0]
	v_fma_mix_f32 v99, v99, v175, v133 op_sel:[0,1,0] op_sel_hi:[0,1,0]
	s_waitcnt vmcnt(8)
;     __device__ __forceinline__ void operator()(f32x4 (&acc)[2][2][4][2], const Unit& u, int wr, int wc, int fr, int fq) const {
;     ...
;             if (u.half == 0) {
; #pragma unroll
;                 for (int m = 0; m < 4; ++m)
; #pragma unroll
;                     for (int bj = 0; bj < 2; ++bj)
; #pragma unroll
;                         for (int j = 0; j < 4; ++j) { acc[ai][bj][m][0][j] *= (float)gt[m][bj][j]; acc[ai][bj][m][1][j] *= (float)gt[m][bj][4 + j]; }
	v_fma_mix_f32 v68, v68, v176, v133 op_sel_hi:[0,1,0]
	v_fma_mix_f32 v69, v69, v176, v133 op_sel:[0,1,0] op_sel_hi:[0,1,0]
	v_fma_mix_f32 v70, v70, v177, v133 op_sel_hi:[0,1,0]
	v_fma_mix_f32 v71, v71, v177, v133 op_sel:[0,1,0] op_sel_hi:[0,1,0]
	v_fma_mix_f32 v64, v64, v178, v133 op_sel_hi:[0,1,0]
	v_fma_mix_f32 v65, v65, v178, v133 op_sel:[0,1,0] op_sel_hi:[0,1,0]
	v_fma_mix_f32 v66, v66, v179, v133 op_sel_hi:[0,1,0]
	v_fma_mix_f32 v67, v67, v179, v133 op_sel:[0,1,0] op_sel_hi:[0,1,0]
	s_waitcnt vmcnt(7)
	v_fma_mix_f32 v60, v60, v180, v133 op_sel_hi:[0,1,0]
	v_fma_mix_f32 v61, v61, v180, v133 op_sel:[0,1,0] op_sel_hi:[0,1,0]
	v_fma_mix_f32 v62, v62, v181, v133 op_sel_hi:[0,1,0]
	v_fma_mix_f32 v63, v63, v181, v133 op_sel:[0,1,0] op_sel_hi:[0,1,0]
	v_fma_mix_f32 v56, v56, v182, v133 op_sel_hi:[0,1,0]
	v_fma_mix_f32 v57, v57, v182, v133 op_sel:[0,1,0] op_sel_hi:[0,1,0]
	v_fma_mix_f32 v58, v58, v183, v133 op_sel_hi:[0,1,0]
	v_fma_mix_f32 v59, v59, v183, v133 op_sel:[0,1,0] op_sel_hi:[0,1,0]
	s_waitcnt vmcnt(6)
	v_fma_mix_f32 v28, v28, v184, v133 op_sel_hi:[0,1,0]
	v_fma_mix_f32 v29, v29, v184, v133 op_sel:[0,1,0] op_sel_hi:[0,1,0]
	v_fma_mix_f32 v30, v30, v185, v133 op_sel_hi:[0,1,0]
	v_fma_mix_f32 v31, v31, v185, v133 op_sel:[0,1,0] op_sel_hi:[0,1,0]
	v_fma_mix_f32 v24, v24, v186, v133 op_sel_hi:[0,1,0]
	v_fma_mix_f32 v25, v25, v186, v133 op_sel:[0,1,0] op_sel_hi:[0,1,0]
	v_fma_mix_f32 v26, v26, v187, v133 op_sel_hi:[0,1,0]
	v_fma_mix_f32 v27, v27, v187, v133 op_sel:[0,1,0] op_sel_hi:[0,1,0]
	s_waitcnt vmcnt(5)
	v_fma_mix_f32 v52, v52, v188, v133 op_sel_hi:[0,1,0]
	v_fma_mix_f32 v53, v53, v188, v133 op_sel:[0,1,0] op_sel_hi:[0,1,0]
	v_fma_mix_f32 v54, v54, v189, v133 op_sel_hi:[0,1,0]
	v_fma_mix_f32 v55, v55, v189, v133 op_sel:[0,1,0] op_sel_hi:[0,1,0]
	v_fma_mix_f32 v48, v48, v190, v133 op_sel_hi:[0,1,0]
	v_fma_mix_f32 v49, v49, v190, v133 op_sel:[0,1,0] op_sel_hi:[0,1,0]
	v_fma_mix_f32 v50, v50, v191, v133 op_sel_hi:[0,1,0]
	v_fma_mix_f32 v51, v51, v191, v133 op_sel:[0,1,0] op_sel_hi:[0,1,0]
	s_waitcnt vmcnt(4)
	v_fma_mix_f32 v20, v20, v192, v133 op_sel_hi:[0,1,0]
	v_fma_mix_f32 v21, v21, v192, v133 op_sel:[0,1,0] op_sel_hi:[0,1,0]
	v_fma_mix_f32 v22, v22, v193, v133 op_sel_hi:[0,1,0]
	v_fma_mix_f32 v23, v23, v193, v133 op_sel:[0,1,0] op_sel_hi:[0,1,0]
	v_fma_mix_f32 v16, v16, v194, v133 op_sel_hi:[0,1,0]
	v_fma_mix_f32 v17, v17, v194, v133 op_sel:[0,1,0] op_sel_hi:[0,1,0]
	v_fma_mix_f32 v18, v18, v195, v133 op_sel_hi:[0,1,0]
	v_fma_mix_f32 v19, v19, v195, v133 op_sel:[0,1,0] op_sel_hi:[0,1,0]
	s_waitcnt vmcnt(3)
	v_fma_mix_f32 v44, v44, v196, v133 op_sel_hi:[0,1,0]
	v_fma_mix_f32 v45, v45, v196, v133 op_sel:[0,1,0] op_sel_hi:[0,1,0]
	v_fma_mix_f32 v46, v46, v197, v133 op_sel_hi:[0,1,0]
	v_fma_mix_f32 v47, v47, v197, v133 op_sel:[0,1,0] op_sel_hi:[0,1,0]
	v_fma_mix_f32 v40, v40, v198, v133 op_sel_hi:[0,1,0]
	v_fma_mix_f32 v41, v41, v198, v133 op_sel:[0,1,0] op_sel_hi:[0,1,0]
	v_fma_mix_f32 v42, v42, v199, v133 op_sel_hi:[0,1,0]
	v_fma_mix_f32 v43, v43, v199, v133 op_sel:[0,1,0] op_sel_hi:[0,1,0]
	s_waitcnt vmcnt(2)
	v_fma_mix_f32 v12, v12, v200, v133 op_sel_hi:[0,1,0]
	v_fma_mix_f32 v13, v13, v200, v133 op_sel:[0,1,0] op_sel_hi:[0,1,0]
	v_fma_mix_f32 v14, v14, v201, v133 op_sel_hi:[0,1,0]
	v_fma_mix_f32 v15, v15, v201, v133 op_sel:[0,1,0] op_sel_hi:[0,1,0]
	v_fma_mix_f32 v8, v8, v202, v133 op_sel_hi:[0,1,0]
	v_fma_mix_f32 v9, v9, v202, v133 op_sel:[0,1,0] op_sel_hi:[0,1,0]
	v_fma_mix_f32 v10, v10, v203, v133 op_sel_hi:[0,1,0]
	v_fma_mix_f32 v11, v11, v203, v133 op_sel:[0,1,0] op_sel_hi:[0,1,0]
	s_waitcnt vmcnt(1)
	v_fma_mix_f32 v36, v36, v204, v133 op_sel_hi:[0,1,0]
	v_fma_mix_f32 v37, v37, v204, v133 op_sel:[0,1,0] op_sel_hi:[0,1,0]
	v_fma_mix_f32 v38, v38, v205, v133 op_sel_hi:[0,1,0]
	v_fma_mix_f32 v39, v39, v205, v133 op_sel:[0,1,0] op_sel_hi:[0,1,0]
	v_fma_mix_f32 v32, v32, v206, v133 op_sel_hi:[0,1,0]
	v_fma_mix_f32 v33, v33, v206, v133 op_sel:[0,1,0] op_sel_hi:[0,1,0]
	v_fma_mix_f32 v34, v34, v207, v133 op_sel_hi:[0,1,0]
	v_fma_mix_f32 v35, v35, v207, v133 op_sel:[0,1,0] op_sel_hi:[0,1,0]
	s_waitcnt vmcnt(0)
	v_fma_mix_f32 v4, v4, v208, v133 op_sel_hi:[0,1,0]
	v_fma_mix_f32 v5, v5, v208, v133 op_sel:[0,1,0] op_sel_hi:[0,1,0]
	v_fma_mix_f32 v6, v6, v209, v133 op_sel_hi:[0,1,0]
	v_fma_mix_f32 v7, v7, v209, v133 op_sel:[0,1,0] op_sel_hi:[0,1,0]
	v_fma_mix_f32 v0, v0, v210, v133 op_sel_hi:[0,1,0]
	v_fma_mix_f32 v1, v1, v210, v133 op_sel:[0,1,0] op_sel_hi:[0,1,0]
	v_fma_mix_f32 v2, v2, v211, v133 op_sel_hi:[0,1,0]
	v_fma_mix_f32 v3, v3, v211, v133 op_sel:[0,1,0] op_sel_hi:[0,1,0]
	s_branch .LBB0_482
;     __device__ __forceinline__ void operator()(f32x4 (&acc)[2][2][4][2], const Unit& u, int wr, int wc, int fr, int fq) const {
;     ...
;             } else {
; #pragma unroll
;                 for (int m = 0; m < 4; ++m) { const size_t row = (size_t)(row0 + ai * HALF + m * 16);
; #pragma unroll
;                     for (int bj = 0; bj < 2; ++bj) { const int col = col0 + bj * HALF;
;                         float o[8];
; #pragma unroll
;                         for (int j = 0; j < 4; ++j) { o[j] = acc[ai][bj][m][0][j] * (float)gt[m][bj][j]; o[4 + j] = acc[ai][bj][m][1][j] * (float)gt[m][bj][4 + j]; }
;                         u32x4 w; w.x = pkg(o[0], o[1]); w.y = pkg(o[2], o[3]); w.z = pkg(o[4], o[5]); w.w = pkg(o[6], o[7]);
;                         *(u32x4*)(MG + row * D + col) = w; } }
.Lg2e_final:
	v_lshl_add_u32 v144, s44, 8, v213
	v_lshl_or_b32 v142, s45, 8, v215
	v_ashrrev_i32_e32 v145, 31, v144
	v_ashrrev_i32_e32 v143, 31, v142
	v_lshlrev_b64 v[144:145], 13, v[144:145]
	v_lshl_add_u64 v[144:145], s[12:13], 0, v[144:145]
	v_lshl_add_u64 v[144:145], v[142:143], 1, v[144:145]
	s_mov_b32 s49, 0
	s_waitcnt vmcnt(14)
	v_fma_mix_f32 v124, v124, v148, v133 op_sel_hi:[0,1,0]
	v_fma_mix_f32 v125, v125, v148, v133 op_sel:[0,1,0] op_sel_hi:[0,1,0]
	v_fma_mix_f32 v126, v126, v149, v133 op_sel_hi:[0,1,0]
	v_fma_mix_f32 v127, v127, v149, v133 op_sel:[0,1,0] op_sel_hi:[0,1,0]
	v_fma_mix_f32 v120, v120, v150, v133 op_sel_hi:[0,1,0]
	v_fma_mix_f32 v121, v121, v150, v133 op_sel:[0,1,0] op_sel_hi:[0,1,0]
	v_fma_mix_f32 v122, v122, v151, v133 op_sel_hi:[0,1,0]
	v_fma_mix_f32 v123, v123, v151, v133 op_sel:[0,1,0] op_sel_hi:[0,1,0]
	v_fma_mix_f32 v92, v92, v152, v133 op_sel_hi:[0,1,0]
	v_fma_mix_f32 v93, v93, v152, v133 op_sel:[0,1,0] op_sel_hi:[0,1,0]
	v_fma_mix_f32 v94, v94, v153, v133 op_sel_hi:[0,1,0]
	v_fma_mix_f32 v95, v95, v153, v133 op_sel:[0,1,0] op_sel_hi:[0,1,0]
	v_fma_mix_f32 v88, v88, v154, v133 op_sel_hi:[0,1,0]
	v_fma_mix_f32 v89, v89, v154, v133 op_sel:[0,1,0] op_sel_hi:[0,1,0]
	v_fma_mix_f32 v90, v90, v155, v133 op_sel_hi:[0,1,0]
	v_fma_mix_f32 v91, v91, v155, v133 op_sel:[0,1,0] op_sel_hi:[0,1,0]
	v_cvt_pk_bf16_f32 v148, v124, v125
	v_cvt_pk_bf16_f32 v149, v126, v127
	v_cvt_pk_bf16_f32 v150, v120, v121
	v_cvt_pk_bf16_f32 v151, v122, v123
	v_cvt_pk_bf16_f32 v152, v92, v93
	v_cvt_pk_bf16_f32 v153, v94, v95
	v_cvt_pk_bf16_f32 v154, v88, v89
	v_cvt_pk_bf16_f32 v155, v90, v91
	global_store_dwordx4 v[144:145], v[148:151], off
	global_store_dwordx4 v[144:145], v[152:155], off offset:256
	s_waitcnt vmcnt(14)
	v_fma_mix_f32 v116, v116, v156, v133 op_sel_hi:[0,1,0]
	v_fma_mix_f32 v117, v117, v156, v133 op_sel:[0,1,0] op_sel_hi:[0,1,0]
	v_fma_mix_f32 v118, v118, v157, v133 op_sel_hi:[0,1,0]
	v_fma_mix_f32 v119, v119, v157, v133 op_sel:[0,1,0] op_sel_hi:[0,1,0]
	v_fma_mix_f32 v112, v112, v158, v133 op_sel_hi:[0,1,0]
	v_fma_mix_f32 v113, v113, v158, v133 op_sel:[0,1,0] op_sel_hi:[0,1,0]
	v_fma_mix_f32 v114, v114, v159, v133 op_sel_hi:[0,1,0]
	v_fma_mix_f32 v115, v115, v159, v133 op_sel:[0,1,0] op_sel_hi:[0,1,0]
	v_fma_mix_f32 v84, v84, v160, v133 op_sel_hi:[0,1,0]
	v_fma_mix_f32 v85, v85, v160, v133 op_sel:[0,1,0] op_sel_hi:[0,1,0]
	v_fma_mix_f32 v86, v86, v161, v133 op_sel_hi:[0,1,0]
	v_fma_mix_f32 v87, v87, v161, v133 op_sel:[0,1,0] op_sel_hi:[0,1,0]
	v_fma_mix_f32 v80, v80, v162, v133 op_sel_hi:[0,1,0]
	v_fma_mix_f32 v81, v81, v162, v133 op_sel:[0,1,0] op_sel_hi:[0,1,0]
	v_fma_mix_f32 v82, v82, v163, v133 op_sel_hi:[0,1,0]
	v_fma_mix_f32 v83, v83, v163, v133 op_sel:[0,1,0] op_sel_hi:[0,1,0]
	v_cvt_pk_bf16_f32 v156, v116, v117
	v_cvt_pk_bf16_f32 v157, v118, v119
	v_cvt_pk_bf16_f32 v158, v112, v113
	v_cvt_pk_bf16_f32 v159, v114, v115
	v_cvt_pk_bf16_f32 v160, v84, v85
	v_cvt_pk_bf16_f32 v161, v86, v87
	v_cvt_pk_bf16_f32 v162, v80, v81
	v_cvt_pk_bf16_f32 v163, v82, v83
	s_mov_b32 s48, 0x20000
	v_lshl_add_u64 v[146:147], v[144:145], 0, s[48:49]
	global_store_dwordx4 v[146:147], v[156:159], off
	global_store_dwordx4 v[146:147], v[160:163], off offset:256
	s_waitcnt vmcnt(14)
	v_fma_mix_f32 v108, v108, v164, v133 op_sel_hi:[0,1,0]
	v_fma_mix_f32 v109, v109, v164, v133 op_sel:[0,1,0] op_sel_hi:[0,1,0]
	v_fma_mix_f32 v110, v110, v165, v133 op_sel_hi:[0,1,0]
	v_fma_mix_f32 v111, v111, v165, v133 op_sel:[0,1,0] op_sel_hi:[0,1,0]
	v_fma_mix_f32 v104, v104, v166, v133 op_sel_hi:[0,1,0]
	v_fma_mix_f32 v105, v105, v166, v133 op_sel:[0,1,0] op_sel_hi:[0,1,0]
	v_fma_mix_f32 v106, v106, v167, v133 op_sel_hi:[0,1,0]
	v_fma_mix_f32 v107, v107, v167, v133 op_sel:[0,1,0] op_sel_hi:[0,1,0]
	v_fma_mix_f32 v76, v76, v168, v133 op_sel_hi:[0,1,0]
	v_fma_mix_f32 v77, v77, v168, v133 op_sel:[0,1,0] op_sel_hi:[0,1,0]
	v_fma_mix_f32 v78, v78, v169, v133 op_sel_hi:[0,1,0]
	v_fma_mix_f32 v79, v79, v169, v133 op_sel:[0,1,0] op_sel_hi:[0,1,0]
	v_fma_mix_f32 v72, v72, v170, v133 op_sel_hi:[0,1,0]
	v_fma_mix_f32 v73, v73, v170, v133 op_sel:[0,1,0] op_sel_hi:[0,1,0]
	v_fma_mix_f32 v74, v74, v171, v133 op_sel_hi:[0,1,0]
	v_fma_mix_f32 v75, v75, v171, v133 op_sel:[0,1,0] op_sel_hi:[0,1,0]
	v_cvt_pk_bf16_f32 v164, v108, v109
	v_cvt_pk_bf16_f32 v165, v110, v111
	v_cvt_pk_bf16_f32 v166, v104, v105
	v_cvt_pk_bf16_f32 v167, v106, v107
	v_cvt_pk_bf16_f32 v168, v76, v77
	v_cvt_pk_bf16_f32 v169, v78, v79
	v_cvt_pk_bf16_f32 v170, v72, v73
	v_cvt_pk_bf16_f32 v171, v74, v75
	s_mov_b32 s48, 0x40000
	v_lshl_add_u64 v[146:147], v[144:145], 0, s[48:49]
	global_store_dwordx4 v[146:147], v[164:167], off
	global_store_dwordx4 v[146:147], v[168:171], off offset:256
	s_waitcnt vmcnt(14)
	v_fma_mix_f32 v100, v100, v172, v133 op_sel_hi:[0,1,0]
	v_fma_mix_f32 v101, v101, v172, v133 op_sel:[0,1,0] op_sel_hi:[0,1,0]
	v_fma_mix_f32 v102, v102, v173, v133 op_sel_hi:[0,1,0]
	v_fma_mix_f32 v103, v103, v173, v133 op_sel:[0,1,0] op_sel_hi:[0,1,0]
	v_fma_mix_f32 v96, v96, v174, v133 op_sel_hi:[0,1,0]
	v_fma_mix_f32 v97, v97, v174, v133 op_sel:[0,1,0] op_sel_hi:[0,1,0]
	v_fma_mix_f32 v98, v98, v175, v133 op_sel_hi:[0,1,0]
	v_fma_mix_f32 v99, v99, v175, v133 op_sel:[0,1,0] op_sel_hi:[0,1,0]
	v_fma_mix_f32 v68, v68, v176, v133 op_sel_hi:[0,1,0]
	v_fma_mix_f32 v69, v69, v176, v133 op_sel:[0,1,0] op_sel_hi:[0,1,0]
	v_fma_mix_f32 v70, v70, v177, v133 op_sel_hi:[0,1,0]
	v_fma_mix_f32 v71, v71, v177, v133 op_sel:[0,1,0] op_sel_hi:[0,1,0]
	v_fma_mix_f32 v64, v64, v178, v133 op_sel_hi:[0,1,0]
	v_fma_mix_f32 v65, v65, v178, v133 op_sel:[0,1,0] op_sel_hi:[0,1,0]
	v_fma_mix_f32 v66, v66, v179, v133 op_sel_hi:[0,1,0]
	v_fma_mix_f32 v67, v67, v179, v133 op_sel:[0,1,0] op_sel_hi:[0,1,0]
	v_cvt_pk_bf16_f32 v172, v100, v101
	v_cvt_pk_bf16_f32 v173, v102, v103
	v_cvt_pk_bf16_f32 v174, v96, v97
	v_cvt_pk_bf16_f32 v175, v98, v99
	v_cvt_pk_bf16_f32 v176, v68, v69
	v_cvt_pk_bf16_f32 v177, v70, v71
	v_cvt_pk_bf16_f32 v178, v64, v65
	v_cvt_pk_bf16_f32 v179, v66, v67
	s_mov_b32 s48, 0x60000
	v_lshl_add_u64 v[146:147], v[144:145], 0, s[48:49]
	global_store_dwordx4 v[146:147], v[172:175], off
	global_store_dwordx4 v[146:147], v[176:179], off offset:256
	s_waitcnt vmcnt(14)
;     __device__ __forceinline__ void operator()(f32x4 (&acc)[2][2][4][2], const Unit& u, int wr, int wc, int fr, int fq) const {
;     ...
;             } else {
; #pragma unroll
;                 for (int m = 0; m < 4; ++m) { const size_t row = (size_t)(row0 + ai * HALF + m * 16);
; #pragma unroll
;                     for (int bj = 0; bj < 2; ++bj) { const int col = col0 + bj * HALF;
;                         float o[8];
; #pragma unroll
;                         for (int j = 0; j < 4; ++j) { o[j] = acc[ai][bj][m][0][j] * (float)gt[m][bj][j]; o[4 + j] = acc[ai][bj][m][1][j] * (float)gt[m][bj][4 + j]; }
;                         u32x4 w; w.x = pkg(o[0], o[1]); w.y = pkg(o[2], o[3]); w.z = pkg(o[4], o[5]); w.w = pkg(o[6], o[7]);
;                         *(u32x4*)(MG + row * D + col) = w; } }
	v_fma_mix_f32 v60, v60, v180, v133 op_sel_hi:[0,1,0]
	v_fma_mix_f32 v61, v61, v180, v133 op_sel:[0,1,0] op_sel_hi:[0,1,0]
	v_fma_mix_f32 v62, v62, v181, v133 op_sel_hi:[0,1,0]
	v_fma_mix_f32 v63, v63, v181, v133 op_sel:[0,1,0] op_sel_hi:[0,1,0]
	v_fma_mix_f32 v56, v56, v182, v133 op_sel_hi:[0,1,0]
	v_fma_mix_f32 v57, v57, v182, v133 op_sel:[0,1,0] op_sel_hi:[0,1,0]
	v_fma_mix_f32 v58, v58, v183, v133 op_sel_hi:[0,1,0]
	v_fma_mix_f32 v59, v59, v183, v133 op_sel:[0,1,0] op_sel_hi:[0,1,0]
	v_fma_mix_f32 v28, v28, v184, v133 op_sel_hi:[0,1,0]
	v_fma_mix_f32 v29, v29, v184, v133 op_sel:[0,1,0] op_sel_hi:[0,1,0]
	v_fma_mix_f32 v30, v30, v185, v133 op_sel_hi:[0,1,0]
	v_fma_mix_f32 v31, v31, v185, v133 op_sel:[0,1,0] op_sel_hi:[0,1,0]
	v_fma_mix_f32 v24, v24, v186, v133 op_sel_hi:[0,1,0]
	v_fma_mix_f32 v25, v25, v186, v133 op_sel:[0,1,0] op_sel_hi:[0,1,0]
	v_fma_mix_f32 v26, v26, v187, v133 op_sel_hi:[0,1,0]
	v_fma_mix_f32 v27, v27, v187, v133 op_sel:[0,1,0] op_sel_hi:[0,1,0]
	v_cvt_pk_bf16_f32 v180, v60, v61
	v_cvt_pk_bf16_f32 v181, v62, v63
	v_cvt_pk_bf16_f32 v182, v56, v57
	v_cvt_pk_bf16_f32 v183, v58, v59
	v_cvt_pk_bf16_f32 v184, v28, v29
	v_cvt_pk_bf16_f32 v185, v30, v31
	v_cvt_pk_bf16_f32 v186, v24, v25
	v_cvt_pk_bf16_f32 v187, v26, v27
	s_mov_b32 s48, 0x100000
	v_lshl_add_u64 v[146:147], v[144:145], 0, s[48:49]
	global_store_dwordx4 v[146:147], v[180:183], off
	global_store_dwordx4 v[146:147], v[184:187], off offset:256
	s_waitcnt vmcnt(14)
	v_fma_mix_f32 v52, v52, v188, v133 op_sel_hi:[0,1,0]
	v_fma_mix_f32 v53, v53, v188, v133 op_sel:[0,1,0] op_sel_hi:[0,1,0]
	v_fma_mix_f32 v54, v54, v189, v133 op_sel_hi:[0,1,0]
	v_fma_mix_f32 v55, v55, v189, v133 op_sel:[0,1,0] op_sel_hi:[0,1,0]
	v_fma_mix_f32 v48, v48, v190, v133 op_sel_hi:[0,1,0]
	v_fma_mix_f32 v49, v49, v190, v133 op_sel:[0,1,0] op_sel_hi:[0,1,0]
	v_fma_mix_f32 v50, v50, v191, v133 op_sel_hi:[0,1,0]
	v_fma_mix_f32 v51, v51, v191, v133 op_sel:[0,1,0] op_sel_hi:[0,1,0]
	v_fma_mix_f32 v20, v20, v192, v133 op_sel_hi:[0,1,0]
	v_fma_mix_f32 v21, v21, v192, v133 op_sel:[0,1,0] op_sel_hi:[0,1,0]
	v_fma_mix_f32 v22, v22, v193, v133 op_sel_hi:[0,1,0]
	v_fma_mix_f32 v23, v23, v193, v133 op_sel:[0,1,0] op_sel_hi:[0,1,0]
	v_fma_mix_f32 v16, v16, v194, v133 op_sel_hi:[0,1,0]
	v_fma_mix_f32 v17, v17, v194, v133 op_sel:[0,1,0] op_sel_hi:[0,1,0]
	v_fma_mix_f32 v18, v18, v195, v133 op_sel_hi:[0,1,0]
	v_fma_mix_f32 v19, v19, v195, v133 op_sel:[0,1,0] op_sel_hi:[0,1,0]
	v_cvt_pk_bf16_f32 v188, v52, v53
	v_cvt_pk_bf16_f32 v189, v54, v55
	v_cvt_pk_bf16_f32 v190, v48, v49
	v_cvt_pk_bf16_f32 v191, v50, v51
	v_cvt_pk_bf16_f32 v192, v20, v21
	v_cvt_pk_bf16_f32 v193, v22, v23
	v_cvt_pk_bf16_f32 v194, v16, v17
	v_cvt_pk_bf16_f32 v195, v18, v19
	s_mov_b32 s48, 0x120000
	v_lshl_add_u64 v[146:147], v[144:145], 0, s[48:49]
	global_store_dwordx4 v[146:147], v[188:191], off
	global_store_dwordx4 v[146:147], v[192:195], off offset:256
	s_waitcnt vmcnt(14)
	v_fma_mix_f32 v44, v44, v196, v133 op_sel_hi:[0,1,0]
	v_fma_mix_f32 v45, v45, v196, v133 op_sel:[0,1,0] op_sel_hi:[0,1,0]
	v_fma_mix_f32 v46, v46, v197, v133 op_sel_hi:[0,1,0]
	v_fma_mix_f32 v47, v47, v197, v133 op_sel:[0,1,0] op_sel_hi:[0,1,0]
	v_fma_mix_f32 v40, v40, v198, v133 op_sel_hi:[0,1,0]
	v_fma_mix_f32 v41, v41, v198, v133 op_sel:[0,1,0] op_sel_hi:[0,1,0]
	v_fma_mix_f32 v42, v42, v199, v133 op_sel_hi:[0,1,0]
	v_fma_mix_f32 v43, v43, v199, v133 op_sel:[0,1,0] op_sel_hi:[0,1,0]
	v_fma_mix_f32 v12, v12, v200, v133 op_sel_hi:[0,1,0]
	v_fma_mix_f32 v13, v13, v200, v133 op_sel:[0,1,0] op_sel_hi:[0,1,0]
	v_fma_mix_f32 v14, v14, v201, v133 op_sel_hi:[0,1,0]
	v_fma_mix_f32 v15, v15, v201, v133 op_sel:[0,1,0] op_sel_hi:[0,1,0]
	v_fma_mix_f32 v8, v8, v202, v133 op_sel_hi:[0,1,0]
	v_fma_mix_f32 v9, v9, v202, v133 op_sel:[0,1,0] op_sel_hi:[0,1,0]
	v_fma_mix_f32 v10, v10, v203, v133 op_sel_hi:[0,1,0]
	v_fma_mix_f32 v11, v11, v203, v133 op_sel:[0,1,0] op_sel_hi:[0,1,0]
	v_cvt_pk_bf16_f32 v196, v44, v45
	v_cvt_pk_bf16_f32 v197, v46, v47
	v_cvt_pk_bf16_f32 v198, v40, v41
	v_cvt_pk_bf16_f32 v199, v42, v43
	v_cvt_pk_bf16_f32 v200, v12, v13
	v_cvt_pk_bf16_f32 v201, v14, v15
	v_cvt_pk_bf16_f32 v202, v8, v9
	v_cvt_pk_bf16_f32 v203, v10, v11
	s_mov_b32 s48, 0x140000
	v_lshl_add_u64 v[146:147], v[144:145], 0, s[48:49]
	global_store_dwordx4 v[146:147], v[196:199], off
	global_store_dwordx4 v[146:147], v[200:203], off offset:256
	s_waitcnt vmcnt(14)
	v_fma_mix_f32 v36, v36, v204, v133 op_sel_hi:[0,1,0]
	v_fma_mix_f32 v37, v37, v204, v133 op_sel:[0,1,0] op_sel_hi:[0,1,0]
	v_fma_mix_f32 v38, v38, v205, v133 op_sel_hi:[0,1,0]
	v_fma_mix_f32 v39, v39, v205, v133 op_sel:[0,1,0] op_sel_hi:[0,1,0]
	v_fma_mix_f32 v32, v32, v206, v133 op_sel_hi:[0,1,0]
	v_fma_mix_f32 v33, v33, v206, v133 op_sel:[0,1,0] op_sel_hi:[0,1,0]
	v_fma_mix_f32 v34, v34, v207, v133 op_sel_hi:[0,1,0]
	v_fma_mix_f32 v35, v35, v207, v133 op_sel:[0,1,0] op_sel_hi:[0,1,0]
	v_fma_mix_f32 v4, v4, v208, v133 op_sel_hi:[0,1,0]
	v_fma_mix_f32 v5, v5, v208, v133 op_sel:[0,1,0] op_sel_hi:[0,1,0]
	v_fma_mix_f32 v6, v6, v209, v133 op_sel_hi:[0,1,0]
	v_fma_mix_f32 v7, v7, v209, v133 op_sel:[0,1,0] op_sel_hi:[0,1,0]
	v_fma_mix_f32 v0, v0, v210, v133 op_sel_hi:[0,1,0]
	v_fma_mix_f32 v1, v1, v210, v133 op_sel:[0,1,0] op_sel_hi:[0,1,0]
	v_fma_mix_f32 v2, v2, v211, v133 op_sel_hi:[0,1,0]
	v_fma_mix_f32 v3, v3, v211, v133 op_sel:[0,1,0] op_sel_hi:[0,1,0]
	v_cvt_pk_bf16_f32 v204, v36, v37
	v_cvt_pk_bf16_f32 v205, v38, v39
	v_cvt_pk_bf16_f32 v206, v32, v33
	v_cvt_pk_bf16_f32 v207, v34, v35
	v_cvt_pk_bf16_f32 v208, v4, v5
	v_cvt_pk_bf16_f32 v209, v6, v7
	v_cvt_pk_bf16_f32 v210, v0, v1
	v_cvt_pk_bf16_f32 v211, v2, v3
	s_mov_b32 s48, 0x160000
	v_lshl_add_u64 v[146:147], v[144:145], 0, s[48:49]
	global_store_dwordx4 v[146:147], v[204:207], off
	global_store_dwordx4 v[146:147], v[208:211], off offset:256
